# prologue x->bf16 row loop and final RMSNorm row loop: all 16 row loads issued up front (counted vmcnt) instead of load-wait-store round trips; norm_final gains held in registers
# speedup vs baseline: 1.0118x; 1.0118x over previous
.LBB0_32:
	v_lshlrev_b32_e32 v34, 4, v24
	v_lshlrev_b32_e32 v38, 3, v24
	v_add_u32_e32 v35, 0x1000, v34
	v_add_u32_e32 v36, 0x2000, v34
	v_add_u32_e32 v37, 0x3000, v34
	v_add_u32_e32 v39, 0x1000, v38
	s_waitcnt lgkmcnt(0)
	global_load_dwordx4 v[64:67], v34, s[20:21]
	global_load_dwordx4 v[68:71], v34, s[20:21] offset:1024
	global_load_dwordx4 v[72:75], v34, s[20:21] offset:2048
	global_load_dwordx4 v[76:79], v34, s[20:21] offset:3072
	global_load_dwordx4 v[80:83], v35, s[20:21]
	global_load_dwordx4 v[84:87], v35, s[20:21] offset:1024
	global_load_dwordx4 v[88:91], v35, s[20:21] offset:2048
	global_load_dwordx4 v[92:95], v35, s[20:21] offset:3072
	global_load_dwordx4 v[96:99], v36, s[20:21]
	global_load_dwordx4 v[100:103], v36, s[20:21] offset:1024
	global_load_dwordx4 v[104:107], v36, s[20:21] offset:2048
	global_load_dwordx4 v[108:111], v36, s[20:21] offset:3072
	global_load_dwordx4 v[112:115], v37, s[20:21]
	global_load_dwordx4 v[116:119], v37, s[20:21] offset:1024
	global_load_dwordx4 v[120:123], v37, s[20:21] offset:2048
	global_load_dwordx4 v[124:127], v37, s[20:21] offset:3072
	s_lshl_b64 s[36:37], s[18:19], 13
	s_add_u32 s36, s3, s36
	s_addc_u32 s37, s5, s37
	s_waitcnt vmcnt(15)
	v_cvt_pk_bf16_f32 v0, v64, v65
	v_cvt_pk_bf16_f32 v1, v66, v67
	global_store_dwordx2 v38, v[0:1], s[36:37]
	v_lshlrev_b32_e32 v4, 16, v0
	v_and_b32_e32 v5, 0xffff0000, v0
	v_lshlrev_b32_e32 v6, 16, v1
	v_and_b32_e32 v7, 0xffff0000, v1
	v_mul_f32_e32 v5, v5, v5
	v_mul_f32_e32 v7, v7, v7
	v_fmac_f32_e32 v5, v4, v4
	v_fmac_f32_e32 v7, v6, v6
	v_add_f32_e32 v8, v5, v7
	s_waitcnt vmcnt(15)
	v_cvt_pk_bf16_f32 v2, v68, v69
	v_cvt_pk_bf16_f32 v3, v70, v71
	global_store_dwordx2 v38, v[2:3], s[36:37] offset:512
	v_lshlrev_b32_e32 v4, 16, v2
	v_and_b32_e32 v5, 0xffff0000, v2
	v_lshlrev_b32_e32 v6, 16, v3
	v_and_b32_e32 v7, 0xffff0000, v3
	v_mul_f32_e32 v5, v5, v5
	v_mul_f32_e32 v7, v7, v7
	v_fmac_f32_e32 v5, v4, v4
	v_fmac_f32_e32 v7, v6, v6
	v_add_f32_e32 v5, v5, v7
	v_add_f32_e32 v8, v8, v5
	s_waitcnt vmcnt(15)
	v_cvt_pk_bf16_f32 v0, v72, v73
	v_cvt_pk_bf16_f32 v1, v74, v75
	global_store_dwordx2 v38, v[0:1], s[36:37] offset:1024
	v_lshlrev_b32_e32 v4, 16, v0
	v_and_b32_e32 v5, 0xffff0000, v0
	v_lshlrev_b32_e32 v6, 16, v1
	v_and_b32_e32 v7, 0xffff0000, v1
	v_mul_f32_e32 v5, v5, v5
	v_mul_f32_e32 v7, v7, v7
	v_fmac_f32_e32 v5, v4, v4
	v_fmac_f32_e32 v7, v6, v6
	v_add_f32_e32 v5, v5, v7
	v_add_f32_e32 v8, v8, v5
	s_waitcnt vmcnt(15)
	v_cvt_pk_bf16_f32 v2, v76, v77
	v_cvt_pk_bf16_f32 v3, v78, v79
	global_store_dwordx2 v38, v[2:3], s[36:37] offset:1536
	v_lshlrev_b32_e32 v4, 16, v2
	v_and_b32_e32 v5, 0xffff0000, v2
	v_lshlrev_b32_e32 v6, 16, v3
	v_and_b32_e32 v7, 0xffff0000, v3
	v_mul_f32_e32 v5, v5, v5
	v_mul_f32_e32 v7, v7, v7
	v_fmac_f32_e32 v5, v4, v4
	v_fmac_f32_e32 v7, v6, v6
	v_add_f32_e32 v5, v5, v7
	v_add_f32_e32 v8, v8, v5
	s_waitcnt vmcnt(15)
	v_cvt_pk_bf16_f32 v0, v80, v81
	v_cvt_pk_bf16_f32 v1, v82, v83
	global_store_dwordx2 v38, v[0:1], s[36:37] offset:2048
	v_lshlrev_b32_e32 v4, 16, v0
	v_and_b32_e32 v5, 0xffff0000, v0
	v_lshlrev_b32_e32 v6, 16, v1
	v_and_b32_e32 v7, 0xffff0000, v1
	v_mul_f32_e32 v5, v5, v5
	v_mul_f32_e32 v7, v7, v7
	v_fmac_f32_e32 v5, v4, v4
	v_fmac_f32_e32 v7, v6, v6
	v_add_f32_e32 v5, v5, v7
	v_add_f32_e32 v8, v8, v5
	s_waitcnt vmcnt(15)
	v_cvt_pk_bf16_f32 v2, v84, v85
	v_cvt_pk_bf16_f32 v3, v86, v87
	global_store_dwordx2 v38, v[2:3], s[36:37] offset:2560
	v_lshlrev_b32_e32 v4, 16, v2
	v_and_b32_e32 v5, 0xffff0000, v2
	v_lshlrev_b32_e32 v6, 16, v3
	v_and_b32_e32 v7, 0xffff0000, v3
	v_mul_f32_e32 v5, v5, v5
	v_mul_f32_e32 v7, v7, v7
	v_fmac_f32_e32 v5, v4, v4
	v_fmac_f32_e32 v7, v6, v6
	v_add_f32_e32 v5, v5, v7
	v_add_f32_e32 v8, v8, v5
	s_waitcnt vmcnt(15)
	v_cvt_pk_bf16_f32 v0, v88, v89
	v_cvt_pk_bf16_f32 v1, v90, v91
	global_store_dwordx2 v38, v[0:1], s[36:37] offset:3072
	v_lshlrev_b32_e32 v4, 16, v0
	v_and_b32_e32 v5, 0xffff0000, v0
	v_lshlrev_b32_e32 v6, 16, v1
	v_and_b32_e32 v7, 0xffff0000, v1
	v_mul_f32_e32 v5, v5, v5
	v_mul_f32_e32 v7, v7, v7
	v_fmac_f32_e32 v5, v4, v4
	v_fmac_f32_e32 v7, v6, v6
	v_add_f32_e32 v5, v5, v7
	v_add_f32_e32 v8, v8, v5
	s_waitcnt vmcnt(15)
	v_cvt_pk_bf16_f32 v2, v92, v93
	v_cvt_pk_bf16_f32 v3, v94, v95
	global_store_dwordx2 v38, v[2:3], s[36:37] offset:3584
	v_lshlrev_b32_e32 v4, 16, v2
	v_and_b32_e32 v5, 0xffff0000, v2
	v_lshlrev_b32_e32 v6, 16, v3
	v_and_b32_e32 v7, 0xffff0000, v3
	v_mul_f32_e32 v5, v5, v5
	v_mul_f32_e32 v7, v7, v7
	v_fmac_f32_e32 v5, v4, v4
	v_fmac_f32_e32 v7, v6, v6
	v_add_f32_e32 v5, v5, v7
	v_add_f32_e32 v8, v8, v5
	s_waitcnt vmcnt(15)
	v_cvt_pk_bf16_f32 v0, v96, v97
	v_cvt_pk_bf16_f32 v1, v98, v99
	global_store_dwordx2 v39, v[0:1], s[36:37]
	v_lshlrev_b32_e32 v4, 16, v0
	v_and_b32_e32 v5, 0xffff0000, v0
	v_lshlrev_b32_e32 v6, 16, v1
	v_and_b32_e32 v7, 0xffff0000, v1
	v_mul_f32_e32 v5, v5, v5
	v_mul_f32_e32 v7, v7, v7
	v_fmac_f32_e32 v5, v4, v4
	v_fmac_f32_e32 v7, v6, v6
	v_add_f32_e32 v5, v5, v7
	v_add_f32_e32 v8, v8, v5
	s_waitcnt vmcnt(15)
	v_cvt_pk_bf16_f32 v2, v100, v101
	v_cvt_pk_bf16_f32 v3, v102, v103
	global_store_dwordx2 v39, v[2:3], s[36:37] offset:512
	v_lshlrev_b32_e32 v4, 16, v2
	v_and_b32_e32 v5, 0xffff0000, v2
	v_lshlrev_b32_e32 v6, 16, v3
	v_and_b32_e32 v7, 0xffff0000, v3
	v_mul_f32_e32 v5, v5, v5
	v_mul_f32_e32 v7, v7, v7
	v_fmac_f32_e32 v5, v4, v4
	v_fmac_f32_e32 v7, v6, v6
	v_add_f32_e32 v5, v5, v7
	v_add_f32_e32 v8, v8, v5
	s_waitcnt vmcnt(15)
	v_cvt_pk_bf16_f32 v0, v104, v105
	v_cvt_pk_bf16_f32 v1, v106, v107
	global_store_dwordx2 v39, v[0:1], s[36:37] offset:1024
	v_lshlrev_b32_e32 v4, 16, v0
	v_and_b32_e32 v5, 0xffff0000, v0
	v_lshlrev_b32_e32 v6, 16, v1
	v_and_b32_e32 v7, 0xffff0000, v1
	v_mul_f32_e32 v5, v5, v5
	v_mul_f32_e32 v7, v7, v7
	v_fmac_f32_e32 v5, v4, v4
	v_fmac_f32_e32 v7, v6, v6
	v_add_f32_e32 v5, v5, v7
	v_add_f32_e32 v8, v8, v5
	s_waitcnt vmcnt(15)
	v_cvt_pk_bf16_f32 v2, v108, v109
	v_cvt_pk_bf16_f32 v3, v110, v111
	global_store_dwordx2 v39, v[2:3], s[36:37] offset:1536
	v_lshlrev_b32_e32 v4, 16, v2
	v_and_b32_e32 v5, 0xffff0000, v2
	v_lshlrev_b32_e32 v6, 16, v3
	v_and_b32_e32 v7, 0xffff0000, v3
	v_mul_f32_e32 v5, v5, v5
	v_mul_f32_e32 v7, v7, v7
	v_fmac_f32_e32 v5, v4, v4
	v_fmac_f32_e32 v7, v6, v6
	v_add_f32_e32 v5, v5, v7
	v_add_f32_e32 v8, v8, v5
	s_waitcnt vmcnt(15)
	v_cvt_pk_bf16_f32 v0, v112, v113
	v_cvt_pk_bf16_f32 v1, v114, v115
	global_store_dwordx2 v39, v[0:1], s[36:37] offset:2048
	v_lshlrev_b32_e32 v4, 16, v0
	v_and_b32_e32 v5, 0xffff0000, v0
	v_lshlrev_b32_e32 v6, 16, v1
	v_and_b32_e32 v7, 0xffff0000, v1
	v_mul_f32_e32 v5, v5, v5
	v_mul_f32_e32 v7, v7, v7
	v_fmac_f32_e32 v5, v4, v4
	v_fmac_f32_e32 v7, v6, v6
	v_add_f32_e32 v5, v5, v7
	v_add_f32_e32 v8, v8, v5
	s_waitcnt vmcnt(15)
	v_cvt_pk_bf16_f32 v2, v116, v117
	v_cvt_pk_bf16_f32 v3, v118, v119
	global_store_dwordx2 v39, v[2:3], s[36:37] offset:2560
	v_lshlrev_b32_e32 v4, 16, v2
	v_and_b32_e32 v5, 0xffff0000, v2
	v_lshlrev_b32_e32 v6, 16, v3
	v_and_b32_e32 v7, 0xffff0000, v3
	v_mul_f32_e32 v5, v5, v5
	v_mul_f32_e32 v7, v7, v7
	v_fmac_f32_e32 v5, v4, v4
	v_fmac_f32_e32 v7, v6, v6
	v_add_f32_e32 v5, v5, v7
	v_add_f32_e32 v8, v8, v5
	s_waitcnt vmcnt(15)
	v_cvt_pk_bf16_f32 v0, v120, v121
	v_cvt_pk_bf16_f32 v1, v122, v123
	global_store_dwordx2 v39, v[0:1], s[36:37] offset:3072
	v_lshlrev_b32_e32 v4, 16, v0
	v_and_b32_e32 v5, 0xffff0000, v0
	v_lshlrev_b32_e32 v6, 16, v1
	v_and_b32_e32 v7, 0xffff0000, v1
	v_mul_f32_e32 v5, v5, v5
	v_mul_f32_e32 v7, v7, v7
	v_fmac_f32_e32 v5, v4, v4
	v_fmac_f32_e32 v7, v6, v6
	v_add_f32_e32 v5, v5, v7
	v_add_f32_e32 v8, v8, v5
	s_waitcnt vmcnt(15)
	v_cvt_pk_bf16_f32 v2, v124, v125
	v_cvt_pk_bf16_f32 v3, v126, v127
	global_store_dwordx2 v39, v[2:3], s[36:37] offset:3584
	v_lshlrev_b32_e32 v4, 16, v2
	v_and_b32_e32 v5, 0xffff0000, v2
	v_lshlrev_b32_e32 v6, 16, v3
	v_and_b32_e32 v7, 0xffff0000, v3
	v_mul_f32_e32 v5, v5, v5
	v_mul_f32_e32 v7, v7, v7
	v_fmac_f32_e32 v5, v4, v4
	v_fmac_f32_e32 v7, v6, v6
	v_add_f32_e32 v5, v5, v7
	v_add_f32_e32 v8, v8, v5
	v_lshlrev_b32_e32 v9, 2, v26
	ds_bpermute_b32 v10, v9, v8
	s_waitcnt lgkmcnt(0)
	v_add_f32_e32 v8, v8, v10
	v_lshlrev_b32_e32 v9, 2, v27
	ds_bpermute_b32 v10, v9, v8
	s_waitcnt lgkmcnt(0)
	v_add_f32_e32 v8, v8, v10
	v_lshlrev_b32_e32 v9, 2, v28
	ds_bpermute_b32 v10, v9, v8
	s_waitcnt lgkmcnt(0)
	v_add_f32_e32 v8, v8, v10
	v_lshlrev_b32_e32 v9, 2, v29
	ds_bpermute_b32 v10, v9, v8
	s_waitcnt lgkmcnt(0)
	v_add_f32_e32 v8, v8, v10
	v_lshlrev_b32_e32 v9, 2, v30
	ds_bpermute_b32 v10, v9, v8
	s_waitcnt lgkmcnt(0)
	v_add_f32_e32 v8, v8, v10
	v_lshlrev_b32_e32 v9, 2, v31
	ds_bpermute_b32 v10, v9, v8
	s_waitcnt lgkmcnt(0)
	v_add_f32_e32 v8, v8, v10
	v_cmp_eq_u32_e32 vcc, 0, v24
	s_and_saveexec_b64 s[20:21], vcc
	s_cbranch_execz .LBB0_29
	v_mul_f32_e32 v0, 0x4b800000, v8
	v_trunc_f32_e32 v0, v0
	v_mul_f32_e32 v1, 0x2f800000, v0
	v_floor_f32_e32 v1, v1
	v_fmac_f32_e32 v0, 0xcf800000, v1
	v_cvt_u32_f32_e32 v0, v0
	v_cvt_u32_f32_e32 v1, v1
	s_lshl_b64 s[18:19], s[18:19], 3
	s_add_u32 s18, s22, s18
	s_addc_u32 s19, s23, s19
	global_store_dwordx2 v32, v[0:1], s[18:19]
	s_branch .LBB0_29

.LBB0_3299:
	s_cmp_gt_i32 s82, 19
	s_cselect_b64 s[4:5], -1, 0
	s_xor_b64 s[0:1], s[0:1], -1
	s_or_b64 s[0:1], s[4:5], s[0:1]
	s_and_b64 vcc, exec, s[0:1]
	s_cbranch_vccnz .LBB0_3303
	s_lshl_b32 s0, s2, 3
	s_add_i32 s0, s75, s0
	s_cmpk_gt_i32 s0, 0x20ff
	s_cbranch_scc1 .LBB0_3303
	s_ashr_i32 s1, s0, 31
	s_lshl_b32 s2, s88, 3
	s_lshl_b64 s[4:5], s[0:1], 3
	s_add_u32 s14, s4, 0x9e1ef000
	s_addc_u32 s15, s5, 0
	s_ashr_i32 s3, s2, 31
	s_lshl_b64 s[4:5], s[2:3], 3
	s_lshl_b64 s[6:7], s[0:1], 13
	s_lshl_b64 s[8:9], s[2:3], 13
	s_lshl_b64 s[10:11], s[0:1], 14
	s_add_u32 s10, s78, s10
	s_addc_u32 s11, s79, s11
	s_lshl_b64 s[12:13], s[2:3], 14
	s_waitcnt lgkmcnt(0)
	v_mov_b32_e32 v1, 0
	v_mov_b32_e32 v8, 0x358637bd
	s_mov_b32 s1, 0x800000
	s_mov_b32 s3, 0x37d00000
	s_movk_i32 s16, 0x1000
	s_mov_b32 s17, 0x37d01000
	s_movk_i32 s18, 0x2000
	s_movk_i32 s19, 0x3000
	v_mbcnt_lo_u32_b32 v0, -1, 0
	v_mbcnt_hi_u32_b32 v0, -1, v0
	v_lshlrev_b32_e32 v2, 4, v0
	v_lshlrev_b32_e32 v6, 3, v0
	v_add_u32_e32 v3, 0x1000, v2
	v_add_u32_e32 v4, 0x2000, v2
	v_add_u32_e32 v5, 0x3000, v2
	v_add_u32_e32 v7, 0x1000, v6
	global_load_dwordx4 v[64:67], v2, s[76:77]
	global_load_dwordx4 v[68:71], v2, s[76:77] offset:1024
	global_load_dwordx4 v[72:75], v2, s[76:77] offset:2048
	global_load_dwordx4 v[76:79], v2, s[76:77] offset:3072
	global_load_dwordx4 v[80:83], v3, s[76:77]
	global_load_dwordx4 v[84:87], v3, s[76:77] offset:1024
	global_load_dwordx4 v[88:91], v3, s[76:77] offset:2048
	global_load_dwordx4 v[92:95], v3, s[76:77] offset:3072
	global_load_dwordx4 v[96:99], v4, s[76:77]
	global_load_dwordx4 v[100:103], v4, s[76:77] offset:1024
	global_load_dwordx4 v[104:107], v4, s[76:77] offset:2048
	global_load_dwordx4 v[108:111], v4, s[76:77] offset:3072
	global_load_dwordx4 v[112:115], v5, s[76:77]
	global_load_dwordx4 v[116:119], v5, s[76:77] offset:1024
	global_load_dwordx4 v[120:123], v5, s[76:77] offset:2048
	global_load_dwordx4 v[124:127], v5, s[76:77] offset:3072
.Lfin_row:
	s_add_u32 s20, s80, s14
	s_addc_u32 s21, s81, s15
	global_load_dwordx2 v[14:15], v1, s[20:21]
	s_add_u32 s20, s80, s6
	s_addc_u32 s21, s81, s7
	s_add_u32 s20, s20, 0x37d00000
	s_addc_u32 s21, s21, 0
	global_load_dwordx2 v[32:33], v6, s[20:21]
	global_load_dwordx2 v[34:35], v6, s[20:21] offset:512
	global_load_dwordx2 v[36:37], v6, s[20:21] offset:1024
	global_load_dwordx2 v[38:39], v6, s[20:21] offset:1536
	global_load_dwordx2 v[40:41], v6, s[20:21] offset:2048
	global_load_dwordx2 v[42:43], v6, s[20:21] offset:2560
	global_load_dwordx2 v[44:45], v6, s[20:21] offset:3072
	global_load_dwordx2 v[46:47], v6, s[20:21] offset:3584
	global_load_dwordx2 v[48:49], v7, s[20:21]
	global_load_dwordx2 v[50:51], v7, s[20:21] offset:512
	global_load_dwordx2 v[52:53], v7, s[20:21] offset:1024
	global_load_dwordx2 v[54:55], v7, s[20:21] offset:1536
	global_load_dwordx2 v[56:57], v7, s[20:21] offset:2048
	global_load_dwordx2 v[58:59], v7, s[20:21] offset:2560
	global_load_dwordx2 v[60:61], v7, s[20:21] offset:3072
	global_load_dwordx2 v[62:63], v7, s[20:21] offset:3584
	s_add_i32 s0, s0, s2
	s_add_u32 s14, s14, s4
	s_addc_u32 s15, s15, s5
	s_add_u32 s6, s6, s8
	s_addc_u32 s7, s7, s9
	s_waitcnt vmcnt(16)
	v_ffbh_u32_e32 v9, v15
	v_min_u32_e32 v9, 32, v9
	v_lshlrev_b64 v[14:15], v9, v[14:15]
	v_min_u32_e32 v10, 1, v14
	v_or_b32_e32 v10, v15, v10
	v_cvt_f32_u32_e32 v10, v10
	v_sub_u32_e32 v9, 32, v9
	v_ldexp_f32 v0, v10, v9
	v_mul_f32_e32 v0, 0x33800000, v0
	v_fmamk_f32 v0, v0, 0x39800000, v8
	v_mul_f32_e32 v10, 0x4b800000, v0
	v_cmp_gt_f32_e32 vcc, s1, v0
	s_nop 1
	v_cndmask_b32_e32 v0, v0, v10, vcc
	v_rsq_f32_e32 v0, v0
	s_nop 0
	v_mul_f32_e32 v10, 0x45800000, v0
	v_cndmask_b32_e32 v0, v0, v10, vcc
	s_waitcnt vmcnt(15)
	v_lshlrev_b32_e32 v16, 16, v32
	v_and_b32_e32 v17, 0xffff0000, v32
	v_lshlrev_b32_e32 v18, 16, v33
	v_and_b32_e32 v19, 0xffff0000, v33
	v_pk_mul_f32 v[16:17], v[0:1], v[16:17] op_sel_hi:[0,1]
	v_pk_mul_f32 v[18:19], v[0:1], v[18:19] op_sel_hi:[0,1]
	v_pk_mul_f32 v[20:21], v[64:65], v[16:17]
	v_pk_mul_f32 v[22:23], v[66:67], v[18:19]
	global_store_dwordx4 v2, v[20:23], s[10:11]
	s_waitcnt vmcnt(15)
	v_lshlrev_b32_e32 v24, 16, v34
	v_and_b32_e32 v25, 0xffff0000, v34
	v_lshlrev_b32_e32 v26, 16, v35
	v_and_b32_e32 v27, 0xffff0000, v35
	v_pk_mul_f32 v[24:25], v[0:1], v[24:25] op_sel_hi:[0,1]
	v_pk_mul_f32 v[26:27], v[0:1], v[26:27] op_sel_hi:[0,1]
	v_pk_mul_f32 v[28:29], v[68:69], v[24:25]
	v_pk_mul_f32 v[30:31], v[70:71], v[26:27]
	global_store_dwordx4 v2, v[28:31], s[10:11] offset:1024
	s_waitcnt vmcnt(15)
	v_lshlrev_b32_e32 v16, 16, v36
	v_and_b32_e32 v17, 0xffff0000, v36
	v_lshlrev_b32_e32 v18, 16, v37
	v_and_b32_e32 v19, 0xffff0000, v37
	v_pk_mul_f32 v[16:17], v[0:1], v[16:17] op_sel_hi:[0,1]
	v_pk_mul_f32 v[18:19], v[0:1], v[18:19] op_sel_hi:[0,1]
	v_pk_mul_f32 v[20:21], v[72:73], v[16:17]
	v_pk_mul_f32 v[22:23], v[74:75], v[18:19]
	global_store_dwordx4 v2, v[20:23], s[10:11] offset:2048
	s_waitcnt vmcnt(15)
	v_lshlrev_b32_e32 v24, 16, v38
	v_and_b32_e32 v25, 0xffff0000, v38
	v_lshlrev_b32_e32 v26, 16, v39
	v_and_b32_e32 v27, 0xffff0000, v39
	v_pk_mul_f32 v[24:25], v[0:1], v[24:25] op_sel_hi:[0,1]
	v_pk_mul_f32 v[26:27], v[0:1], v[26:27] op_sel_hi:[0,1]
	v_pk_mul_f32 v[28:29], v[76:77], v[24:25]
	v_pk_mul_f32 v[30:31], v[78:79], v[26:27]
	global_store_dwordx4 v2, v[28:31], s[10:11] offset:3072
	s_waitcnt vmcnt(15)
	v_lshlrev_b32_e32 v16, 16, v40
	v_and_b32_e32 v17, 0xffff0000, v40
	v_lshlrev_b32_e32 v18, 16, v41
	v_and_b32_e32 v19, 0xffff0000, v41
	v_pk_mul_f32 v[16:17], v[0:1], v[16:17] op_sel_hi:[0,1]
	v_pk_mul_f32 v[18:19], v[0:1], v[18:19] op_sel_hi:[0,1]
	v_pk_mul_f32 v[20:21], v[80:81], v[16:17]
	v_pk_mul_f32 v[22:23], v[82:83], v[18:19]
	global_store_dwordx4 v3, v[20:23], s[10:11]
	s_waitcnt vmcnt(15)
	v_lshlrev_b32_e32 v24, 16, v42
	v_and_b32_e32 v25, 0xffff0000, v42
	v_lshlrev_b32_e32 v26, 16, v43
	v_and_b32_e32 v27, 0xffff0000, v43
	v_pk_mul_f32 v[24:25], v[0:1], v[24:25] op_sel_hi:[0,1]
	v_pk_mul_f32 v[26:27], v[0:1], v[26:27] op_sel_hi:[0,1]
	v_pk_mul_f32 v[28:29], v[84:85], v[24:25]
	v_pk_mul_f32 v[30:31], v[86:87], v[26:27]
	global_store_dwordx4 v3, v[28:31], s[10:11] offset:1024
	s_waitcnt vmcnt(15)
	v_lshlrev_b32_e32 v16, 16, v44
	v_and_b32_e32 v17, 0xffff0000, v44
	v_lshlrev_b32_e32 v18, 16, v45
	v_and_b32_e32 v19, 0xffff0000, v45
	v_pk_mul_f32 v[16:17], v[0:1], v[16:17] op_sel_hi:[0,1]
	v_pk_mul_f32 v[18:19], v[0:1], v[18:19] op_sel_hi:[0,1]
	v_pk_mul_f32 v[20:21], v[88:89], v[16:17]
	v_pk_mul_f32 v[22:23], v[90:91], v[18:19]
	global_store_dwordx4 v3, v[20:23], s[10:11] offset:2048
	s_waitcnt vmcnt(15)
	v_lshlrev_b32_e32 v24, 16, v46
	v_and_b32_e32 v25, 0xffff0000, v46
	v_lshlrev_b32_e32 v26, 16, v47
	v_and_b32_e32 v27, 0xffff0000, v47
	v_pk_mul_f32 v[24:25], v[0:1], v[24:25] op_sel_hi:[0,1]
	v_pk_mul_f32 v[26:27], v[0:1], v[26:27] op_sel_hi:[0,1]
	v_pk_mul_f32 v[28:29], v[92:93], v[24:25]
	v_pk_mul_f32 v[30:31], v[94:95], v[26:27]
	global_store_dwordx4 v3, v[28:31], s[10:11] offset:3072
	s_waitcnt vmcnt(15)
	v_lshlrev_b32_e32 v16, 16, v48
	v_and_b32_e32 v17, 0xffff0000, v48
	v_lshlrev_b32_e32 v18, 16, v49
	v_and_b32_e32 v19, 0xffff0000, v49
	v_pk_mul_f32 v[16:17], v[0:1], v[16:17] op_sel_hi:[0,1]
	v_pk_mul_f32 v[18:19], v[0:1], v[18:19] op_sel_hi:[0,1]
	v_pk_mul_f32 v[20:21], v[96:97], v[16:17]
	v_pk_mul_f32 v[22:23], v[98:99], v[18:19]
	global_store_dwordx4 v4, v[20:23], s[10:11]
	s_waitcnt vmcnt(15)
	v_lshlrev_b32_e32 v24, 16, v50
	v_and_b32_e32 v25, 0xffff0000, v50
	v_lshlrev_b32_e32 v26, 16, v51
	v_and_b32_e32 v27, 0xffff0000, v51
	v_pk_mul_f32 v[24:25], v[0:1], v[24:25] op_sel_hi:[0,1]
	v_pk_mul_f32 v[26:27], v[0:1], v[26:27] op_sel_hi:[0,1]
	v_pk_mul_f32 v[28:29], v[100:101], v[24:25]
	v_pk_mul_f32 v[30:31], v[102:103], v[26:27]
	global_store_dwordx4 v4, v[28:31], s[10:11] offset:1024
	s_waitcnt vmcnt(15)
	v_lshlrev_b32_e32 v16, 16, v52
	v_and_b32_e32 v17, 0xffff0000, v52
	v_lshlrev_b32_e32 v18, 16, v53
	v_and_b32_e32 v19, 0xffff0000, v53
	v_pk_mul_f32 v[16:17], v[0:1], v[16:17] op_sel_hi:[0,1]
	v_pk_mul_f32 v[18:19], v[0:1], v[18:19] op_sel_hi:[0,1]
	v_pk_mul_f32 v[20:21], v[104:105], v[16:17]
	v_pk_mul_f32 v[22:23], v[106:107], v[18:19]
	global_store_dwordx4 v4, v[20:23], s[10:11] offset:2048
	s_waitcnt vmcnt(15)
	v_lshlrev_b32_e32 v24, 16, v54
	v_and_b32_e32 v25, 0xffff0000, v54
	v_lshlrev_b32_e32 v26, 16, v55
	v_and_b32_e32 v27, 0xffff0000, v55
	v_pk_mul_f32 v[24:25], v[0:1], v[24:25] op_sel_hi:[0,1]
	v_pk_mul_f32 v[26:27], v[0:1], v[26:27] op_sel_hi:[0,1]
	v_pk_mul_f32 v[28:29], v[108:109], v[24:25]
	v_pk_mul_f32 v[30:31], v[110:111], v[26:27]
	global_store_dwordx4 v4, v[28:31], s[10:11] offset:3072
	s_waitcnt vmcnt(15)
	v_lshlrev_b32_e32 v16, 16, v56
	v_and_b32_e32 v17, 0xffff0000, v56
	v_lshlrev_b32_e32 v18, 16, v57
	v_and_b32_e32 v19, 0xffff0000, v57
	v_pk_mul_f32 v[16:17], v[0:1], v[16:17] op_sel_hi:[0,1]
	v_pk_mul_f32 v[18:19], v[0:1], v[18:19] op_sel_hi:[0,1]
	v_pk_mul_f32 v[20:21], v[112:113], v[16:17]
	v_pk_mul_f32 v[22:23], v[114:115], v[18:19]
	global_store_dwordx4 v5, v[20:23], s[10:11]
	s_waitcnt vmcnt(15)
	v_lshlrev_b32_e32 v24, 16, v58
	v_and_b32_e32 v25, 0xffff0000, v58
	v_lshlrev_b32_e32 v26, 16, v59
	v_and_b32_e32 v27, 0xffff0000, v59
	v_pk_mul_f32 v[24:25], v[0:1], v[24:25] op_sel_hi:[0,1]
	v_pk_mul_f32 v[26:27], v[0:1], v[26:27] op_sel_hi:[0,1]
	v_pk_mul_f32 v[28:29], v[116:117], v[24:25]
	v_pk_mul_f32 v[30:31], v[118:119], v[26:27]
	global_store_dwordx4 v5, v[28:31], s[10:11] offset:1024
	s_waitcnt vmcnt(15)
	v_lshlrev_b32_e32 v16, 16, v60
	v_and_b32_e32 v17, 0xffff0000, v60
	v_lshlrev_b32_e32 v18, 16, v61
	v_and_b32_e32 v19, 0xffff0000, v61
	v_pk_mul_f32 v[16:17], v[0:1], v[16:17] op_sel_hi:[0,1]
	v_pk_mul_f32 v[18:19], v[0:1], v[18:19] op_sel_hi:[0,1]
	v_pk_mul_f32 v[20:21], v[120:121], v[16:17]
	v_pk_mul_f32 v[22:23], v[122:123], v[18:19]
	global_store_dwordx4 v5, v[20:23], s[10:11] offset:2048
	s_waitcnt vmcnt(15)
	v_lshlrev_b32_e32 v24, 16, v62
	v_and_b32_e32 v25, 0xffff0000, v62
	v_lshlrev_b32_e32 v26, 16, v63
	v_and_b32_e32 v27, 0xffff0000, v63
	v_pk_mul_f32 v[24:25], v[0:1], v[24:25] op_sel_hi:[0,1]
	v_pk_mul_f32 v[26:27], v[0:1], v[26:27] op_sel_hi:[0,1]
	v_pk_mul_f32 v[28:29], v[124:125], v[24:25]
	v_pk_mul_f32 v[30:31], v[126:127], v[26:27]
	global_store_dwordx4 v5, v[28:31], s[10:11] offset:3072
	s_add_u32 s10, s10, s12
	s_addc_u32 s11, s11, s13
	s_cmpk_lt_i32 s0, 0x2100
	s_cbranch_scc1 .Lfin_row
